# seam 5 also group-local: FF1 reads only its own group's Wout output; the cross-group write-after-read on buffer H is covered by a completion counter that FF1 checks before its first store to H
# speedup vs baseline: 1.0190x; 1.0057x over previous
; #define LAS __attribute__((address_space(3)))
; __device__ __forceinline__ unsigned xb_ld(unsigned* p) { return __hip_atomic_load(p, __ATOMIC_RELAXED, __HIP_MEMORY_SCOPE_AGENT); }
; __device__ __forceinline__ unsigned xb_add(unsigned* p, unsigned v) { return __hip_atomic_fetch_add(p, v, __ATOMIC_RELAXED, __HIP_MEMORY_SCOPE_AGENT); }
; __device__ __forceinline__ unsigned xb_xcc_id() { return (unsigned)__builtin_amdgcn_s_getreg((3 << 11) | 20) & 0xFu; }
; __device__ __forceinline__ void grid_barrier(unsigned* barw, int k, volatile LAS unsigned* st) {
;     asm volatile("s_waitcnt vmcnt(0)" ::: "memory");
;     __syncthreads();
;     if (threadIdx.x == 0) {
;         __builtin_amdgcn_s_waitcnt(0);
;         const unsigned x = xb_xcc_id();
;         unsigned nloc = st[0], nx = st[1];
;         if (nloc == 0u) {
;             const unsigned G = gridDim.x;
;             for (;;) { unsigned sum = 0u, cnt = 0u, mine = 0u;
; #pragma unroll
;                 for (unsigned j = 0; j < 16; ++j) { const unsigned c = xb_ld(barw + 64 * j); sum += c; cnt += (c > 0u) ? 1u : 0u; mine = (j == x) ? c : mine; }
;                 if (sum == G) { nloc = mine; nx = cnt; break; }
;                 __builtin_amdgcn_s_sleep(1); }
;             st[0] = nloc; st[1] = nx;
;         }
;         unsigned* sb = barw + 1024 + k * 2304;
;         const unsigned old = xb_add(sb + 64 * x, 1u);
;         if (old + 1u == nloc) {
;             __builtin_amdgcn_fence(__ATOMIC_RELEASE, "agent");
;             asm volatile("s_waitcnt vmcnt(0)" ::: "memory");
;             const unsigned og = xb_add(sb + 2048, 1u);
;             if (og + 1u == nx) xb_add(sb + 2112, 1u);
;             else while (xb_ld(sb + 2112) == 0u) __builtin_amdgcn_s_sleep(1);
;             __builtin_amdgcn_fence(__ATOMIC_ACQUIRE, "agent");
;             xb_add(sb + 1024 + 64 * x, 1u);
;             asm volatile("s_waitcnt vmcnt(0)" ::: "memory");
;         } else {
;             while (xb_ld(sb + 1024 + 64 * x) == 0u) __builtin_amdgcn_s_sleep(1);
;             __builtin_amdgcn_fence(__ATOMIC_ACQUIRE, "agent");
;             asm volatile("s_waitcnt vmcnt(0)" ::: "memory");
;         }
;     }
;     __syncthreads();
; }
.LBB0_960:
	v_readlane_b32 s2, v254, 0
	v_readlane_b32 s3, v254, 1
	s_cmp_gt_i32 s3, 6
	s_cselect_b64 s[72:73], -1, 0
	s_and_b64 s[0:1], s[0:1], s[72:73]
	s_andn2_b64 vcc, exec, s[0:1]
	s_cbranch_vccnz .LBB0_989
	s_waitcnt vmcnt(0)
	s_waitcnt vmcnt(0) lgkmcnt(0)
	s_barrier
	s_mov_b64 s[74:75], exec
	v_readlane_b32 s0, v254, 2
	v_readlane_b32 s1, v254, 3
	s_and_b64 s[0:1], s[74:75], s[0:1]
	s_mov_b64 exec, s[0:1]
	s_cbranch_execz .LBB0_988
	s_add_u32 s4, s78, 0x12800
	s_addc_u32 s5, s79, 0
	v_mov_b32_e32 v0, 0
	v_mov_b32_e32 v1, 1
	global_atomic_add v0, v1, s[4:5]
	s_and_b32 s0, s88, 7
	s_cmp_lg_u32 s0, 0
	s_cbranch_scc1 .Lgb0_orig
	s_waitcnt vmcnt(0) lgkmcnt(0)
	s_and_b32 s0, s70, 7
	s_lshl_b32 s0, s0, 8
	s_add_i32 s0, s0, 0x10c00
	s_add_u32 s4, s78, s0
	s_addc_u32 s5, s79, 0
	s_lshr_b32 s6, s88, 3
	s_getreg_b32 s8, hwreg(HW_REG_XCC_ID, 0, 4)
	s_lshl_b32 s8, 1, s8
	v_mov_b32_e32 v0, 0
	v_mov_b32_e32 v1, s8
	global_atomic_or v2, v0, v1, s[4:5] offset:64 sc0
	s_waitcnt vmcnt(0)
	v_mov_b32_e32 v1, 1
	global_atomic_add v2, v0, v1, s[4:5] sc0
	s_waitcnt vmcnt(0)
	v_readfirstlane_b32 s7, v2
	s_add_i32 s7, s7, 1
	s_cmp_ge_u32 s7, s6
	s_cbranch_scc1 .Lgb0_all1

;     __device__ bool next(int i, Unit& u) const { const long L = (long)i * G + c; if (L >= 128) return false; u.pm = (int)L & 31; u.pn = u.pm >> 4; u.koff = ((int)L >> 5) * 1024; return true; }
;     __host__ __device__ bool next(int i, Unit& u) const {
;         const long L = (long)i * G + c; if (L >= nwg) return false;
;         int wgid = (int)L; { const int q = nwg / NXCD, r = nwg % NXCD, xcd = wgid % NXCD, off = wgid / NXCD; wgid = (xcd < r ? xcd * (q + 1) : r * (q + 1) + (xcd - r) * q) + off; }
;         const int nig = WGM * nN, gid = wgid / nig, fm = gid * WGM, gsz = (nM - fm) < WGM ? (nM - fm) : WGM;
;         u.pm = fm + ((wgid % nig) % gsz); u.pn = (wgid % nig) / gsz; u.koff = 0; return true;
; __global__ void __launch_bounds__(NWAVES * 64, 2) fwd_kernel(Args args) {
;     ...
;     if (IN(6)) {
;         pg8::Gemm g{(const bf16_t*)(ws + WS_X2B), (const bf16_t*)(ws + WS_WFF1), T, FF, DM, DM, DM};
;         pg8::StaticOrder So; So.init(T, FF, G, (int)blockIdx.x);
;         EpiFF1 E{(const float*)(ws + WS_SSQP), (bf16_t*)(ws + WS_H)};
;         pg8::gemm_phase<EpiFF1, pg8::StaticOrder, true, true>(lds, g, So, E);
.LBB0_989:
	s_mov_b32 s98, 0
	s_add_u32 s100, s78, 0x12800
	s_addc_u32 s101, s79, 0
	v_readlane_b32 s0, v254, 0
	v_readlane_b32 s1, v254, 1
	s_cmp_lt_i32 s0, 7
	s_cselect_b64 s[0:1], -1, 0
	s_and_b64 s[0:1], s[0:1], s[72:73]
	s_andn2_b64 vcc, exec, s[0:1]
	s_cbranch_vccnz .LBB0_1014
	s_cmpk_gt_i32 s70, 0x7ff
	v_readfirstlane_b32 s4, v184
	s_cbranch_scc1 .LBB0_1014
	s_ashr_i32 s14, s70, 31
	s_lshr_b32 s2, s14, 29
	s_add_i32 s7, s70, s2
	s_and_b32 s2, s7, -8
	s_sub_i32 s6, s70, s2
	s_cmp_gt_i32 s6, -1
	s_cbranch_scc0 .LBB0_993
	s_lshl_b32 s5, s6, 8
	s_ashr_i32 s2, s7, 3
	s_cbranch_execz .LBB0_994
	s_branch .LBB0_995

;     __device__ __forceinline__ void operator()(const f32x4 (&acc)[2][2][4][2], const pg8::Unit& u, int wr, int wc, int fr, int fq) const {
;         f32x4 sq[2][4];
; #pragma unroll
;         for (int ai = 0; ai < 2; ++ai)
; #pragma unroll
;             for (int m = 0; m < 4; ++m) sq[ai][m] = *(const f32x4*)(ssqp + (size_t)(u.pm * 256 + ai * 128 + wr * 64 + m * 16 + fr) * 4);
;         __builtin_amdgcn_sched_barrier(0);
; #pragma unroll
;         for (int ai = 0; ai < 2; ++ai)
; #pragma unroll
;             for (int m = 0; m < 4; ++m) {
;                 const int row = u.pm * 256 + ai * 128 + wr * 64 + m * 16 + fr;
;                 const float tot = (sq[ai][m].x + sq[ai][m].y) + (sq[ai][m].z + sq[ai][m].w);
;                 const float rn = rsqrtf(tot * (1.f / 1024.f) + EPS);
; #pragma unroll
;                 for (int bj = 0; bj < 2; ++bj) {
;                     float y[8];
; #pragma unroll
;                     for (int n = 0; n < 2; ++n)
; #pragma unroll
;                         for (int e = 0; e < 4; ++e) { const float h = fmaxf(acc[ai][bj][m][n][e] * rn, 0.f); y[n * 4 + e] = h * h; }
;                     store8(H + (size_t)row * FF + u.pn * 256 + 128 * bj + 32 * wc + 8 * fq, y);
;                 }
.LBB0_1010:
	s_cmp_eq_u32 s98, 1
	s_cbranch_scc1 .Lh_ok
.Lh_poll:
	v_mov_b32_e32 v128, 0
	global_load_dword v128, v128, s[100:101] sc1
	s_waitcnt vmcnt(0)
	v_readfirstlane_b32 s99, v128
	s_cmp_ge_u32 s99, s88
	s_cbranch_scc1 .Lh_set
	s_sleep 1
	s_branch .Lh_poll
.Lh_set:
	s_mov_b32 s98, 1

; __global__ void __launch_bounds__(NWAVES * 64, 2) fwd_kernel(Args args) {
	.amdhsa_kernel _Z10fwd_kernel4Args
		.amdhsa_group_segment_fixed_size 0
		.amdhsa_private_segment_fixed_size 0
		.amdhsa_kernarg_size 408
		.amdhsa_user_sgpr_count 2
		.amdhsa_user_sgpr_dispatch_ptr 0
		.amdhsa_user_sgpr_queue_ptr 0
		.amdhsa_user_sgpr_kernarg_segment_ptr 1
		.amdhsa_user_sgpr_dispatch_id 0
		.amdhsa_user_sgpr_kernarg_preload_length 0
		.amdhsa_user_sgpr_kernarg_preload_offset 0
		.amdhsa_user_sgpr_private_segment_size 0
		.amdhsa_uses_dynamic_stack 0
		.amdhsa_enable_private_segment 0
		.amdhsa_system_sgpr_workgroup_id_x 1
		.amdhsa_system_sgpr_workgroup_id_y 0
		.amdhsa_system_sgpr_workgroup_id_z 0
		.amdhsa_system_sgpr_workgroup_info 0
		.amdhsa_system_vgpr_workitem_id 2
		.amdhsa_next_free_vgpr 256
		.amdhsa_next_free_sgpr 102
		.amdhsa_accum_offset 256
		.amdhsa_reserve_vcc 1
		.amdhsa_float_round_mode_32 0
		.amdhsa_float_round_mode_16_64 0
		.amdhsa_float_denorm_mode_32 3
		.amdhsa_float_denorm_mode_16_64 3
		.amdhsa_dx10_clamp 1
		.amdhsa_ieee_mode 1
		.amdhsa_fp16_overflow 0
		.amdhsa_tg_split 0
		.amdhsa_exception_fp_ieee_invalid_op 0
		.amdhsa_exception_fp_denorm_src 0
		.amdhsa_exception_fp_ieee_div_zero 0
		.amdhsa_exception_fp_ieee_overflow 0
		.amdhsa_exception_fp_ieee_underflow 0
		.amdhsa_exception_fp_ieee_inexact 0
		.amdhsa_exception_int_div_zero 0
	.end_amdhsa_kernel

; __global__ void __launch_bounds__(NWAVES * 64, 2) fwd_kernel(Args args) {
amdhsa.kernels:
  - .agpr_count:     0
    .args:
      - .offset:         0
        .size:           152
        .value_kind:     by_value
      - .offset:         152
        .size:           4
        .value_kind:     hidden_block_count_x
      - .offset:         156
        .size:           4
        .value_kind:     hidden_block_count_y
      - .offset:         160
        .size:           4
        .value_kind:     hidden_block_count_z
      - .offset:         164
        .size:           2
        .value_kind:     hidden_group_size_x
      - .offset:         166
        .size:           2
        .value_kind:     hidden_group_size_y
      - .offset:         168
        .size:           2
        .value_kind:     hidden_group_size_z
      - .offset:         170
        .size:           2
        .value_kind:     hidden_remainder_x
      - .offset:         172
        .size:           2
        .value_kind:     hidden_remainder_y
      - .offset:         174
        .size:           2
        .value_kind:     hidden_remainder_z
      - .offset:         192
        .size:           8
        .value_kind:     hidden_global_offset_x
      - .offset:         200
        .size:           8
        .value_kind:     hidden_global_offset_y
      - .offset:         208
        .size:           8
        .value_kind:     hidden_global_offset_z
      - .offset:         216
        .size:           2
        .value_kind:     hidden_grid_dims
      - .offset:         240
        .size:           8
        .value_kind:     hidden_multigrid_sync_arg
      - .offset:         272
        .size:           4
        .value_kind:     hidden_dynamic_lds_size
    .group_segment_fixed_size: 0
    .kernarg_segment_align: 8
    .kernarg_segment_size: 408
    .language:       OpenCL C
    .language_version:
      - 2
      - 0
    .max_flat_workgroup_size: 512
    .name:           _Z10fwd_kernel4Args
    .private_segment_fixed_size: 0
    .sgpr_count:     108
    .sgpr_spill_count: 81
    .symbol:         _Z10fwd_kernel4Args.kd
    .uniform_work_group_size: 1
    .uses_dynamic_stack: false
    .vgpr_count:     256
    .vgpr_spill_count: 0
    .wavefront_size: 64
